# layer 0 MG->WO barrier replaced by completion counters: one L2 write-back per XCD for round 1, per-workgroup for the 16 round-2 tiles; WO waits by wave 0 only
# speedup vs baseline: 1.0165x; 1.0151x over previous
.Lmgepi_last:
	v_mov_b64_e32 v[210:211], v[214:215]
	global_load_dwordx4 v[144:147], v[210:211], off
	global_load_dwordx4 v[148:151], v[210:211], off offset:256
	s_mov_b64 s[98:99], 0x36000
	v_lshl_add_u64 v[210:211], v[214:215], 0, s[98:99]
	global_load_dwordx4 v[152:155], v[210:211], off
	global_load_dwordx4 v[156:159], v[210:211], off offset:256
	s_mov_b64 s[98:99], 0x6c000
	v_lshl_add_u64 v[210:211], v[214:215], 0, s[98:99]
	global_load_dwordx4 v[160:163], v[210:211], off
	global_load_dwordx4 v[164:167], v[210:211], off offset:256
	s_mov_b64 s[98:99], 0xa2000
	v_lshl_add_u64 v[210:211], v[214:215], 0, s[98:99]
	global_load_dwordx4 v[170:173], v[210:211], off
	global_load_dwordx4 v[174:177], v[210:211], off offset:256
	s_waitcnt vmcnt(0)
	v_mov_b64_e32 v[210:211], v[216:217]
	v_lshlrev_b32_e32 v178, 16, v144
	v_and_b32_e32 v144, 0xffff0000, v144
	v_lshlrev_b32_e32 v179, 16, v145
	v_and_b32_e32 v145, 0xffff0000, v145
	v_lshlrev_b32_e32 v180, 16, v146
	v_and_b32_e32 v146, 0xffff0000, v146
	v_lshlrev_b32_e32 v181, 16, v147
	v_and_b32_e32 v147, 0xffff0000, v147
	v_mul_f32_e32 v178, 0xbfb8aa3b, v178
	v_mul_f32_e32 v144, 0xbfb8aa3b, v144
	v_mul_f32_e32 v179, 0xbfb8aa3b, v179
	v_mul_f32_e32 v145, 0xbfb8aa3b, v145
	v_mul_f32_e32 v180, 0xbfb8aa3b, v180
	v_mul_f32_e32 v146, 0xbfb8aa3b, v146
	v_mul_f32_e32 v181, 0xbfb8aa3b, v181
	v_mul_f32_e32 v147, 0xbfb8aa3b, v147
	v_exp_f32_e32 v178, v178
	v_exp_f32_e32 v144, v144
	v_exp_f32_e32 v179, v179
	v_exp_f32_e32 v145, v145
	v_exp_f32_e32 v180, v180
	v_exp_f32_e32 v146, v146
	v_exp_f32_e32 v181, v181
	v_exp_f32_e32 v147, v147
	v_add_f32_e32 v178, 1.0, v178
	v_add_f32_e32 v144, 1.0, v144
	v_add_f32_e32 v179, 1.0, v179
	v_add_f32_e32 v145, 1.0, v145
	v_add_f32_e32 v180, 1.0, v180
	v_add_f32_e32 v146, 1.0, v146
	v_add_f32_e32 v181, 1.0, v181
	v_add_f32_e32 v147, 1.0, v147
	v_rcp_f32_e32 v178, v178
	v_rcp_f32_e32 v144, v144
	v_rcp_f32_e32 v179, v179
	v_rcp_f32_e32 v145, v145
	v_rcp_f32_e32 v180, v180
	v_rcp_f32_e32 v146, v146
	v_rcp_f32_e32 v181, v181
	v_rcp_f32_e32 v147, v147
	s_nop 0
	v_mul_f32_e32 v186, v128, v178
	v_mul_f32_e32 v187, v129, v144
	v_mul_f32_e32 v188, v130, v179
	v_mul_f32_e32 v189, v131, v145
	v_mul_f32_e32 v190, v124, v180
	v_mul_f32_e32 v191, v125, v146
	v_mul_f32_e32 v192, v126, v181
	v_mul_f32_e32 v193, v127, v147
	v_cvt_pk_bf16_f32 v144, v186, v187
	v_cvt_pk_bf16_f32 v145, v188, v189
	v_cvt_pk_bf16_f32 v146, v190, v191
	v_cvt_pk_bf16_f32 v147, v192, v193
	global_store_dwordx4 v[210:211], v[144:147], off
	v_lshlrev_b32_e32 v178, 16, v148
	v_and_b32_e32 v148, 0xffff0000, v148
	v_lshlrev_b32_e32 v179, 16, v149
	v_and_b32_e32 v149, 0xffff0000, v149
	v_lshlrev_b32_e32 v180, 16, v150
	v_and_b32_e32 v150, 0xffff0000, v150
	v_lshlrev_b32_e32 v181, 16, v151
	v_and_b32_e32 v151, 0xffff0000, v151
	v_mul_f32_e32 v178, 0xbfb8aa3b, v178
	v_mul_f32_e32 v148, 0xbfb8aa3b, v148
	v_mul_f32_e32 v179, 0xbfb8aa3b, v179
	v_mul_f32_e32 v149, 0xbfb8aa3b, v149
	v_mul_f32_e32 v180, 0xbfb8aa3b, v180
	v_mul_f32_e32 v150, 0xbfb8aa3b, v150
	v_mul_f32_e32 v181, 0xbfb8aa3b, v181
	v_mul_f32_e32 v151, 0xbfb8aa3b, v151
	v_exp_f32_e32 v178, v178
	v_exp_f32_e32 v148, v148
	v_exp_f32_e32 v179, v179
	v_exp_f32_e32 v149, v149
	v_exp_f32_e32 v180, v180
	v_exp_f32_e32 v150, v150
	v_exp_f32_e32 v181, v181
	v_exp_f32_e32 v151, v151
	v_add_f32_e32 v178, 1.0, v178
	v_add_f32_e32 v148, 1.0, v148
	v_add_f32_e32 v179, 1.0, v179
	v_add_f32_e32 v149, 1.0, v149
	v_add_f32_e32 v180, 1.0, v180
	v_add_f32_e32 v150, 1.0, v150
	v_add_f32_e32 v181, 1.0, v181
	v_add_f32_e32 v151, 1.0, v151
	v_rcp_f32_e32 v178, v178
	v_rcp_f32_e32 v148, v148
	v_rcp_f32_e32 v179, v179
	v_rcp_f32_e32 v149, v149
	v_rcp_f32_e32 v180, v180
	v_rcp_f32_e32 v150, v150
	v_rcp_f32_e32 v181, v181
	v_rcp_f32_e32 v151, v151
	s_nop 0
	v_mul_f32_e32 v186, v92, v178
	v_mul_f32_e32 v187, v93, v148
	v_mul_f32_e32 v188, v94, v179
	v_mul_f32_e32 v189, v95, v149
	v_mul_f32_e32 v190, v88, v180
	v_mul_f32_e32 v191, v89, v150
	v_mul_f32_e32 v192, v90, v181
	v_mul_f32_e32 v193, v91, v151
	v_cvt_pk_bf16_f32 v148, v186, v187
	v_cvt_pk_bf16_f32 v149, v188, v189
	v_cvt_pk_bf16_f32 v150, v190, v191
	v_cvt_pk_bf16_f32 v151, v192, v193
	global_store_dwordx4 v[210:211], v[148:151], off offset:256
	s_mov_b64 s[98:99], 0x36000
	v_lshl_add_u64 v[210:211], v[216:217], 0, s[98:99]
	v_lshlrev_b32_e32 v178, 16, v152
	v_and_b32_e32 v152, 0xffff0000, v152
	v_lshlrev_b32_e32 v179, 16, v153
	v_and_b32_e32 v153, 0xffff0000, v153
	v_lshlrev_b32_e32 v180, 16, v154
	v_and_b32_e32 v154, 0xffff0000, v154
	v_lshlrev_b32_e32 v181, 16, v155
	v_and_b32_e32 v155, 0xffff0000, v155
	v_mul_f32_e32 v178, 0xbfb8aa3b, v178
	v_mul_f32_e32 v152, 0xbfb8aa3b, v152
	v_mul_f32_e32 v179, 0xbfb8aa3b, v179
	v_mul_f32_e32 v153, 0xbfb8aa3b, v153
	v_mul_f32_e32 v180, 0xbfb8aa3b, v180
	v_mul_f32_e32 v154, 0xbfb8aa3b, v154
	v_mul_f32_e32 v181, 0xbfb8aa3b, v181
	v_mul_f32_e32 v155, 0xbfb8aa3b, v155
	v_exp_f32_e32 v178, v178
	v_exp_f32_e32 v152, v152
	v_exp_f32_e32 v179, v179
	v_exp_f32_e32 v153, v153
	v_exp_f32_e32 v180, v180
	v_exp_f32_e32 v154, v154
	v_exp_f32_e32 v181, v181
	v_exp_f32_e32 v155, v155
	v_add_f32_e32 v178, 1.0, v178
	v_add_f32_e32 v152, 1.0, v152
	v_add_f32_e32 v179, 1.0, v179
	v_add_f32_e32 v153, 1.0, v153
	v_add_f32_e32 v180, 1.0, v180
	v_add_f32_e32 v154, 1.0, v154
	v_add_f32_e32 v181, 1.0, v181
	v_add_f32_e32 v155, 1.0, v155
	v_rcp_f32_e32 v178, v178
	v_rcp_f32_e32 v152, v152
	v_rcp_f32_e32 v179, v179
	v_rcp_f32_e32 v153, v153
	v_rcp_f32_e32 v180, v180
	v_rcp_f32_e32 v154, v154
	v_rcp_f32_e32 v181, v181
	v_rcp_f32_e32 v155, v155
	s_nop 0
	v_mul_f32_e32 v186, v120, v178
	v_mul_f32_e32 v187, v121, v152
	v_mul_f32_e32 v188, v122, v179
	v_mul_f32_e32 v189, v123, v153
	v_mul_f32_e32 v190, v116, v180
	v_mul_f32_e32 v191, v117, v154
	v_mul_f32_e32 v192, v118, v181
	v_mul_f32_e32 v193, v119, v155
	v_cvt_pk_bf16_f32 v152, v186, v187
	v_cvt_pk_bf16_f32 v153, v188, v189
	v_cvt_pk_bf16_f32 v154, v190, v191
	v_cvt_pk_bf16_f32 v155, v192, v193
	global_store_dwordx4 v[210:211], v[152:155], off
	v_lshlrev_b32_e32 v178, 16, v156
	v_and_b32_e32 v156, 0xffff0000, v156
	v_lshlrev_b32_e32 v179, 16, v157
	v_and_b32_e32 v157, 0xffff0000, v157
	v_lshlrev_b32_e32 v180, 16, v158
	v_and_b32_e32 v158, 0xffff0000, v158
	v_lshlrev_b32_e32 v181, 16, v159
	v_and_b32_e32 v159, 0xffff0000, v159
	v_mul_f32_e32 v178, 0xbfb8aa3b, v178
	v_mul_f32_e32 v156, 0xbfb8aa3b, v156
	v_mul_f32_e32 v179, 0xbfb8aa3b, v179
	v_mul_f32_e32 v157, 0xbfb8aa3b, v157
	v_mul_f32_e32 v180, 0xbfb8aa3b, v180
	v_mul_f32_e32 v158, 0xbfb8aa3b, v158
	v_mul_f32_e32 v181, 0xbfb8aa3b, v181
	v_mul_f32_e32 v159, 0xbfb8aa3b, v159
	v_exp_f32_e32 v178, v178
	v_exp_f32_e32 v156, v156
	v_exp_f32_e32 v179, v179
	v_exp_f32_e32 v157, v157
	v_exp_f32_e32 v180, v180
	v_exp_f32_e32 v158, v158
	v_exp_f32_e32 v181, v181
	v_exp_f32_e32 v159, v159
	v_add_f32_e32 v178, 1.0, v178
	v_add_f32_e32 v156, 1.0, v156
	v_add_f32_e32 v179, 1.0, v179
	v_add_f32_e32 v157, 1.0, v157
	v_add_f32_e32 v180, 1.0, v180
	v_add_f32_e32 v158, 1.0, v158
	v_add_f32_e32 v181, 1.0, v181
	v_add_f32_e32 v159, 1.0, v159
	v_rcp_f32_e32 v178, v178
	v_rcp_f32_e32 v156, v156
	v_rcp_f32_e32 v179, v179
	v_rcp_f32_e32 v157, v157
	v_rcp_f32_e32 v180, v180
	v_rcp_f32_e32 v158, v158
	v_rcp_f32_e32 v181, v181
	v_rcp_f32_e32 v159, v159
	s_nop 0
	v_mul_f32_e32 v186, v84, v178
	v_mul_f32_e32 v187, v85, v156
	v_mul_f32_e32 v188, v86, v179
	v_mul_f32_e32 v189, v87, v157
	v_mul_f32_e32 v190, v80, v180
	v_mul_f32_e32 v191, v81, v158
	v_mul_f32_e32 v192, v82, v181
	v_mul_f32_e32 v193, v83, v159
	v_cvt_pk_bf16_f32 v156, v186, v187
	v_cvt_pk_bf16_f32 v157, v188, v189
	v_cvt_pk_bf16_f32 v158, v190, v191
	v_cvt_pk_bf16_f32 v159, v192, v193
	global_store_dwordx4 v[210:211], v[156:159], off offset:256
	s_mov_b64 s[98:99], 0x6c000
	v_lshl_add_u64 v[210:211], v[216:217], 0, s[98:99]
	v_lshlrev_b32_e32 v178, 16, v160
	v_and_b32_e32 v160, 0xffff0000, v160
	v_lshlrev_b32_e32 v179, 16, v161
	v_and_b32_e32 v161, 0xffff0000, v161
	v_lshlrev_b32_e32 v180, 16, v162
	v_and_b32_e32 v162, 0xffff0000, v162
	v_lshlrev_b32_e32 v181, 16, v163
	v_and_b32_e32 v163, 0xffff0000, v163
	v_mul_f32_e32 v178, 0xbfb8aa3b, v178
	v_mul_f32_e32 v160, 0xbfb8aa3b, v160
	v_mul_f32_e32 v179, 0xbfb8aa3b, v179
	v_mul_f32_e32 v161, 0xbfb8aa3b, v161
	v_mul_f32_e32 v180, 0xbfb8aa3b, v180
	v_mul_f32_e32 v162, 0xbfb8aa3b, v162
	v_mul_f32_e32 v181, 0xbfb8aa3b, v181
	v_mul_f32_e32 v163, 0xbfb8aa3b, v163
	v_exp_f32_e32 v178, v178
	v_exp_f32_e32 v160, v160
	v_exp_f32_e32 v179, v179
	v_exp_f32_e32 v161, v161
	v_exp_f32_e32 v180, v180
	v_exp_f32_e32 v162, v162
	v_exp_f32_e32 v181, v181
	v_exp_f32_e32 v163, v163
	v_add_f32_e32 v178, 1.0, v178
	v_add_f32_e32 v160, 1.0, v160
	v_add_f32_e32 v179, 1.0, v179
	v_add_f32_e32 v161, 1.0, v161
	v_add_f32_e32 v180, 1.0, v180
	v_add_f32_e32 v162, 1.0, v162
	v_add_f32_e32 v181, 1.0, v181
	v_add_f32_e32 v163, 1.0, v163
	v_rcp_f32_e32 v178, v178
	v_rcp_f32_e32 v160, v160
	v_rcp_f32_e32 v179, v179
	v_rcp_f32_e32 v161, v161
	v_rcp_f32_e32 v180, v180
	v_rcp_f32_e32 v162, v162
	v_rcp_f32_e32 v181, v181
	v_rcp_f32_e32 v163, v163
	s_nop 0
	v_mul_f32_e32 v186, v108, v178
	v_mul_f32_e32 v187, v109, v160
	v_mul_f32_e32 v188, v110, v179
	v_mul_f32_e32 v189, v111, v161
	v_mul_f32_e32 v190, v104, v180
	v_mul_f32_e32 v191, v105, v162
	v_mul_f32_e32 v192, v106, v181
	v_mul_f32_e32 v193, v107, v163
	v_cvt_pk_bf16_f32 v160, v186, v187
	v_cvt_pk_bf16_f32 v161, v188, v189
	v_cvt_pk_bf16_f32 v162, v190, v191
	v_cvt_pk_bf16_f32 v163, v192, v193
	global_store_dwordx4 v[210:211], v[160:163], off
	v_lshlrev_b32_e32 v178, 16, v164
	v_and_b32_e32 v164, 0xffff0000, v164
	v_lshlrev_b32_e32 v179, 16, v165
	v_and_b32_e32 v165, 0xffff0000, v165
	v_lshlrev_b32_e32 v180, 16, v166
	v_and_b32_e32 v166, 0xffff0000, v166
	v_lshlrev_b32_e32 v181, 16, v167
	v_and_b32_e32 v167, 0xffff0000, v167
	v_mul_f32_e32 v178, 0xbfb8aa3b, v178
	v_mul_f32_e32 v164, 0xbfb8aa3b, v164
	v_mul_f32_e32 v179, 0xbfb8aa3b, v179
	v_mul_f32_e32 v165, 0xbfb8aa3b, v165
	v_mul_f32_e32 v180, 0xbfb8aa3b, v180
	v_mul_f32_e32 v166, 0xbfb8aa3b, v166
	v_mul_f32_e32 v181, 0xbfb8aa3b, v181
	v_mul_f32_e32 v167, 0xbfb8aa3b, v167
	v_exp_f32_e32 v178, v178
	v_exp_f32_e32 v164, v164
	v_exp_f32_e32 v179, v179
	v_exp_f32_e32 v165, v165
	v_exp_f32_e32 v180, v180
	v_exp_f32_e32 v166, v166
	v_exp_f32_e32 v181, v181
	v_exp_f32_e32 v167, v167
	v_add_f32_e32 v178, 1.0, v178
	v_add_f32_e32 v164, 1.0, v164
	v_add_f32_e32 v179, 1.0, v179
	v_add_f32_e32 v165, 1.0, v165
	v_add_f32_e32 v180, 1.0, v180
	v_add_f32_e32 v166, 1.0, v166
	v_add_f32_e32 v181, 1.0, v181
	v_add_f32_e32 v167, 1.0, v167
	v_rcp_f32_e32 v178, v178
	v_rcp_f32_e32 v164, v164
	v_rcp_f32_e32 v179, v179
	v_rcp_f32_e32 v165, v165
	v_rcp_f32_e32 v180, v180
	v_rcp_f32_e32 v166, v166
	v_rcp_f32_e32 v181, v181
	v_rcp_f32_e32 v167, v167
	s_nop 0
	v_mul_f32_e32 v186, v76, v178
	v_mul_f32_e32 v187, v77, v164
	v_mul_f32_e32 v188, v78, v179
	v_mul_f32_e32 v189, v79, v165
	v_mul_f32_e32 v190, v72, v180
	v_mul_f32_e32 v191, v73, v166
	v_mul_f32_e32 v192, v74, v181
	v_mul_f32_e32 v193, v75, v167
	v_cvt_pk_bf16_f32 v164, v186, v187
	v_cvt_pk_bf16_f32 v165, v188, v189
	v_cvt_pk_bf16_f32 v166, v190, v191
	v_cvt_pk_bf16_f32 v167, v192, v193
	global_store_dwordx4 v[210:211], v[164:167], off offset:256
	s_mov_b64 s[98:99], 0xa2000
	v_lshl_add_u64 v[210:211], v[216:217], 0, s[98:99]
	v_lshlrev_b32_e32 v178, 16, v170
	v_and_b32_e32 v170, 0xffff0000, v170
	v_lshlrev_b32_e32 v179, 16, v171
	v_and_b32_e32 v171, 0xffff0000, v171
	v_lshlrev_b32_e32 v180, 16, v172
	v_and_b32_e32 v172, 0xffff0000, v172
	v_lshlrev_b32_e32 v181, 16, v173
	v_and_b32_e32 v173, 0xffff0000, v173
	v_mul_f32_e32 v178, 0xbfb8aa3b, v178
	v_mul_f32_e32 v170, 0xbfb8aa3b, v170
	v_mul_f32_e32 v179, 0xbfb8aa3b, v179
	v_mul_f32_e32 v171, 0xbfb8aa3b, v171
	v_mul_f32_e32 v180, 0xbfb8aa3b, v180
	v_mul_f32_e32 v172, 0xbfb8aa3b, v172
	v_mul_f32_e32 v181, 0xbfb8aa3b, v181
	v_mul_f32_e32 v173, 0xbfb8aa3b, v173
	v_exp_f32_e32 v178, v178
	v_exp_f32_e32 v170, v170
	v_exp_f32_e32 v179, v179
	v_exp_f32_e32 v171, v171
	v_exp_f32_e32 v180, v180
	v_exp_f32_e32 v172, v172
	v_exp_f32_e32 v181, v181
	v_exp_f32_e32 v173, v173
	v_add_f32_e32 v178, 1.0, v178
	v_add_f32_e32 v170, 1.0, v170
	v_add_f32_e32 v179, 1.0, v179
	v_add_f32_e32 v171, 1.0, v171
	v_add_f32_e32 v180, 1.0, v180
	v_add_f32_e32 v172, 1.0, v172
	v_add_f32_e32 v181, 1.0, v181
	v_add_f32_e32 v173, 1.0, v173
	v_rcp_f32_e32 v178, v178
	v_rcp_f32_e32 v170, v170
	v_rcp_f32_e32 v179, v179
	v_rcp_f32_e32 v171, v171
	v_rcp_f32_e32 v180, v180
	v_rcp_f32_e32 v172, v172
	v_rcp_f32_e32 v181, v181
	v_rcp_f32_e32 v173, v173
	s_nop 0
	v_mul_f32_e32 v186, v100, v178
	v_mul_f32_e32 v187, v101, v170
	v_mul_f32_e32 v188, v102, v179
	v_mul_f32_e32 v189, v103, v171
	v_mul_f32_e32 v190, v96, v180
	v_mul_f32_e32 v191, v97, v172
	v_mul_f32_e32 v192, v98, v181
	v_mul_f32_e32 v193, v99, v173
	v_cvt_pk_bf16_f32 v170, v186, v187
	v_cvt_pk_bf16_f32 v171, v188, v189
	v_cvt_pk_bf16_f32 v172, v190, v191
	v_cvt_pk_bf16_f32 v173, v192, v193
	global_store_dwordx4 v[210:211], v[170:173], off
	v_lshlrev_b32_e32 v178, 16, v174
	v_and_b32_e32 v174, 0xffff0000, v174
	v_lshlrev_b32_e32 v179, 16, v175
	v_and_b32_e32 v175, 0xffff0000, v175
	v_lshlrev_b32_e32 v180, 16, v176
	v_and_b32_e32 v176, 0xffff0000, v176
	v_lshlrev_b32_e32 v181, 16, v177
	v_and_b32_e32 v177, 0xffff0000, v177
	v_mul_f32_e32 v178, 0xbfb8aa3b, v178
	v_mul_f32_e32 v174, 0xbfb8aa3b, v174
	v_mul_f32_e32 v179, 0xbfb8aa3b, v179
	v_mul_f32_e32 v175, 0xbfb8aa3b, v175
	v_mul_f32_e32 v180, 0xbfb8aa3b, v180
	v_mul_f32_e32 v176, 0xbfb8aa3b, v176
	v_mul_f32_e32 v181, 0xbfb8aa3b, v181
	v_mul_f32_e32 v177, 0xbfb8aa3b, v177
	v_exp_f32_e32 v178, v178
	v_exp_f32_e32 v174, v174
	v_exp_f32_e32 v179, v179
	v_exp_f32_e32 v175, v175
	v_exp_f32_e32 v180, v180
	v_exp_f32_e32 v176, v176
	v_exp_f32_e32 v181, v181
	v_exp_f32_e32 v177, v177
	v_add_f32_e32 v178, 1.0, v178
	v_add_f32_e32 v174, 1.0, v174
	v_add_f32_e32 v179, 1.0, v179
	v_add_f32_e32 v175, 1.0, v175
	v_add_f32_e32 v180, 1.0, v180
	v_add_f32_e32 v176, 1.0, v176
	v_add_f32_e32 v181, 1.0, v181
	v_add_f32_e32 v177, 1.0, v177
	v_rcp_f32_e32 v178, v178
	v_rcp_f32_e32 v174, v174
	v_rcp_f32_e32 v179, v179
	v_rcp_f32_e32 v175, v175
	v_rcp_f32_e32 v180, v180
	v_rcp_f32_e32 v176, v176
	v_rcp_f32_e32 v181, v181
	v_rcp_f32_e32 v177, v177
	s_nop 0
	v_mul_f32_e32 v186, v68, v178
	v_mul_f32_e32 v187, v69, v174
	v_mul_f32_e32 v188, v70, v179
	v_mul_f32_e32 v189, v71, v175
	v_mul_f32_e32 v190, v64, v180
	v_mul_f32_e32 v191, v65, v176
	v_mul_f32_e32 v192, v66, v181
	v_mul_f32_e32 v193, v67, v177
	v_cvt_pk_bf16_f32 v174, v186, v187
	v_cvt_pk_bf16_f32 v175, v188, v189
	v_cvt_pk_bf16_f32 v176, v190, v191
	v_cvt_pk_bf16_f32 v177, v192, v193
	global_store_dwordx4 v[210:211], v[174:177], off offset:256
	s_mov_b64 s[98:99], 0x1b0000
	v_lshl_add_u64 v[210:211], v[214:215], 0, s[98:99]
	global_load_dwordx4 v[144:147], v[210:211], off
	global_load_dwordx4 v[148:151], v[210:211], off offset:256
	s_mov_b64 s[98:99], 0x1e6000
	v_lshl_add_u64 v[210:211], v[214:215], 0, s[98:99]
	global_load_dwordx4 v[152:155], v[210:211], off
	global_load_dwordx4 v[156:159], v[210:211], off offset:256
	s_mov_b64 s[98:99], 0x21c000
	v_lshl_add_u64 v[210:211], v[214:215], 0, s[98:99]
	global_load_dwordx4 v[160:163], v[210:211], off
	global_load_dwordx4 v[164:167], v[210:211], off offset:256
	s_mov_b64 s[98:99], 0x252000
	v_lshl_add_u64 v[210:211], v[214:215], 0, s[98:99]
	global_load_dwordx4 v[170:173], v[210:211], off
	global_load_dwordx4 v[174:177], v[210:211], off offset:256
	s_waitcnt vmcnt(0)
	s_mov_b64 s[98:99], 0x1b0000
	v_lshl_add_u64 v[210:211], v[216:217], 0, s[98:99]
	v_lshlrev_b32_e32 v178, 16, v144
	v_and_b32_e32 v144, 0xffff0000, v144
	v_lshlrev_b32_e32 v179, 16, v145
	v_and_b32_e32 v145, 0xffff0000, v145
	v_lshlrev_b32_e32 v180, 16, v146
	v_and_b32_e32 v146, 0xffff0000, v146
	v_lshlrev_b32_e32 v181, 16, v147
	v_and_b32_e32 v147, 0xffff0000, v147
	v_mul_f32_e32 v178, 0xbfb8aa3b, v178
	v_mul_f32_e32 v144, 0xbfb8aa3b, v144
	v_mul_f32_e32 v179, 0xbfb8aa3b, v179
	v_mul_f32_e32 v145, 0xbfb8aa3b, v145
	v_mul_f32_e32 v180, 0xbfb8aa3b, v180
	v_mul_f32_e32 v146, 0xbfb8aa3b, v146
	v_mul_f32_e32 v181, 0xbfb8aa3b, v181
	v_mul_f32_e32 v147, 0xbfb8aa3b, v147
	v_exp_f32_e32 v178, v178
	v_exp_f32_e32 v144, v144
	v_exp_f32_e32 v179, v179
	v_exp_f32_e32 v145, v145
	v_exp_f32_e32 v180, v180
	v_exp_f32_e32 v146, v146
	v_exp_f32_e32 v181, v181
	v_exp_f32_e32 v147, v147
	v_add_f32_e32 v178, 1.0, v178
	v_add_f32_e32 v144, 1.0, v144
	v_add_f32_e32 v179, 1.0, v179
	v_add_f32_e32 v145, 1.0, v145
	v_add_f32_e32 v180, 1.0, v180
	v_add_f32_e32 v146, 1.0, v146
	v_add_f32_e32 v181, 1.0, v181
	v_add_f32_e32 v147, 1.0, v147
	v_rcp_f32_e32 v178, v178
	v_rcp_f32_e32 v144, v144
	v_rcp_f32_e32 v179, v179
	v_rcp_f32_e32 v145, v145
	v_rcp_f32_e32 v180, v180
	v_rcp_f32_e32 v146, v146
	v_rcp_f32_e32 v181, v181
	v_rcp_f32_e32 v147, v147
	s_nop 0
	v_mul_f32_e32 v186, v60, v178
	v_mul_f32_e32 v187, v61, v144
	v_mul_f32_e32 v188, v62, v179
	v_mul_f32_e32 v189, v63, v145
	v_mul_f32_e32 v190, v56, v180
	v_mul_f32_e32 v191, v57, v146
	v_mul_f32_e32 v192, v58, v181
	v_mul_f32_e32 v193, v59, v147
	v_cvt_pk_bf16_f32 v144, v186, v187
	v_cvt_pk_bf16_f32 v145, v188, v189
	v_cvt_pk_bf16_f32 v146, v190, v191
	v_cvt_pk_bf16_f32 v147, v192, v193
	global_store_dwordx4 v[210:211], v[144:147], off
	v_lshlrev_b32_e32 v178, 16, v148
	v_and_b32_e32 v148, 0xffff0000, v148
	v_lshlrev_b32_e32 v179, 16, v149
	v_and_b32_e32 v149, 0xffff0000, v149
	v_lshlrev_b32_e32 v180, 16, v150
	v_and_b32_e32 v150, 0xffff0000, v150
	v_lshlrev_b32_e32 v181, 16, v151
	v_and_b32_e32 v151, 0xffff0000, v151
	v_mul_f32_e32 v178, 0xbfb8aa3b, v178
	v_mul_f32_e32 v148, 0xbfb8aa3b, v148
	v_mul_f32_e32 v179, 0xbfb8aa3b, v179
	v_mul_f32_e32 v149, 0xbfb8aa3b, v149
	v_mul_f32_e32 v180, 0xbfb8aa3b, v180
	v_mul_f32_e32 v150, 0xbfb8aa3b, v150
	v_mul_f32_e32 v181, 0xbfb8aa3b, v181
	v_mul_f32_e32 v151, 0xbfb8aa3b, v151
	v_exp_f32_e32 v178, v178
	v_exp_f32_e32 v148, v148
	v_exp_f32_e32 v179, v179
	v_exp_f32_e32 v149, v149
	v_exp_f32_e32 v180, v180
	v_exp_f32_e32 v150, v150
	v_exp_f32_e32 v181, v181
	v_exp_f32_e32 v151, v151
	v_add_f32_e32 v178, 1.0, v178
	v_add_f32_e32 v148, 1.0, v148
	v_add_f32_e32 v179, 1.0, v179
	v_add_f32_e32 v149, 1.0, v149
	v_add_f32_e32 v180, 1.0, v180
	v_add_f32_e32 v150, 1.0, v150
	v_add_f32_e32 v181, 1.0, v181
	v_add_f32_e32 v151, 1.0, v151
	v_rcp_f32_e32 v178, v178
	v_rcp_f32_e32 v148, v148
	v_rcp_f32_e32 v179, v179
	v_rcp_f32_e32 v149, v149
	v_rcp_f32_e32 v180, v180
	v_rcp_f32_e32 v150, v150
	v_rcp_f32_e32 v181, v181
	v_rcp_f32_e32 v151, v151
	s_nop 0
	v_mul_f32_e32 v186, v28, v178
	v_mul_f32_e32 v187, v29, v148
	v_mul_f32_e32 v188, v30, v179
	v_mul_f32_e32 v189, v31, v149
	v_mul_f32_e32 v190, v24, v180
	v_mul_f32_e32 v191, v25, v150
	v_mul_f32_e32 v192, v26, v181
	v_mul_f32_e32 v193, v27, v151
	v_cvt_pk_bf16_f32 v148, v186, v187
	v_cvt_pk_bf16_f32 v149, v188, v189
	v_cvt_pk_bf16_f32 v150, v190, v191
	v_cvt_pk_bf16_f32 v151, v192, v193
	global_store_dwordx4 v[210:211], v[148:151], off offset:256
	s_mov_b64 s[98:99], 0x1e6000
	v_lshl_add_u64 v[210:211], v[216:217], 0, s[98:99]
	v_lshlrev_b32_e32 v178, 16, v152
	v_and_b32_e32 v152, 0xffff0000, v152
	v_lshlrev_b32_e32 v179, 16, v153
	v_and_b32_e32 v153, 0xffff0000, v153
	v_lshlrev_b32_e32 v180, 16, v154
	v_and_b32_e32 v154, 0xffff0000, v154
	v_lshlrev_b32_e32 v181, 16, v155
	v_and_b32_e32 v155, 0xffff0000, v155
	v_mul_f32_e32 v178, 0xbfb8aa3b, v178
	v_mul_f32_e32 v152, 0xbfb8aa3b, v152
	v_mul_f32_e32 v179, 0xbfb8aa3b, v179
	v_mul_f32_e32 v153, 0xbfb8aa3b, v153
	v_mul_f32_e32 v180, 0xbfb8aa3b, v180
	v_mul_f32_e32 v154, 0xbfb8aa3b, v154
	v_mul_f32_e32 v181, 0xbfb8aa3b, v181
	v_mul_f32_e32 v155, 0xbfb8aa3b, v155
	v_exp_f32_e32 v178, v178
	v_exp_f32_e32 v152, v152
	v_exp_f32_e32 v179, v179
	v_exp_f32_e32 v153, v153
	v_exp_f32_e32 v180, v180
	v_exp_f32_e32 v154, v154
	v_exp_f32_e32 v181, v181
	v_exp_f32_e32 v155, v155
	v_add_f32_e32 v178, 1.0, v178
	v_add_f32_e32 v152, 1.0, v152
	v_add_f32_e32 v179, 1.0, v179
	v_add_f32_e32 v153, 1.0, v153
	v_add_f32_e32 v180, 1.0, v180
	v_add_f32_e32 v154, 1.0, v154
	v_add_f32_e32 v181, 1.0, v181
	v_add_f32_e32 v155, 1.0, v155
	v_rcp_f32_e32 v178, v178
	v_rcp_f32_e32 v152, v152
	v_rcp_f32_e32 v179, v179
	v_rcp_f32_e32 v153, v153
	v_rcp_f32_e32 v180, v180
	v_rcp_f32_e32 v154, v154
	v_rcp_f32_e32 v181, v181
	v_rcp_f32_e32 v155, v155
	s_nop 0
	v_mul_f32_e32 v186, v52, v178
	v_mul_f32_e32 v187, v53, v152
	v_mul_f32_e32 v188, v54, v179
	v_mul_f32_e32 v189, v55, v153
	v_mul_f32_e32 v190, v48, v180
	v_mul_f32_e32 v191, v49, v154
	v_mul_f32_e32 v192, v50, v181
	v_mul_f32_e32 v193, v51, v155
	v_cvt_pk_bf16_f32 v152, v186, v187
	v_cvt_pk_bf16_f32 v153, v188, v189
	v_cvt_pk_bf16_f32 v154, v190, v191
	v_cvt_pk_bf16_f32 v155, v192, v193
	global_store_dwordx4 v[210:211], v[152:155], off
	v_lshlrev_b32_e32 v178, 16, v156
	v_and_b32_e32 v156, 0xffff0000, v156
	v_lshlrev_b32_e32 v179, 16, v157
	v_and_b32_e32 v157, 0xffff0000, v157
	v_lshlrev_b32_e32 v180, 16, v158
	v_and_b32_e32 v158, 0xffff0000, v158
	v_lshlrev_b32_e32 v181, 16, v159
	v_and_b32_e32 v159, 0xffff0000, v159
	v_mul_f32_e32 v178, 0xbfb8aa3b, v178
	v_mul_f32_e32 v156, 0xbfb8aa3b, v156
	v_mul_f32_e32 v179, 0xbfb8aa3b, v179
	v_mul_f32_e32 v157, 0xbfb8aa3b, v157
	v_mul_f32_e32 v180, 0xbfb8aa3b, v180
	v_mul_f32_e32 v158, 0xbfb8aa3b, v158
	v_mul_f32_e32 v181, 0xbfb8aa3b, v181
	v_mul_f32_e32 v159, 0xbfb8aa3b, v159
	v_exp_f32_e32 v178, v178
	v_exp_f32_e32 v156, v156
	v_exp_f32_e32 v179, v179
	v_exp_f32_e32 v157, v157
	v_exp_f32_e32 v180, v180
	v_exp_f32_e32 v158, v158
	v_exp_f32_e32 v181, v181
	v_exp_f32_e32 v159, v159
	v_add_f32_e32 v178, 1.0, v178
	v_add_f32_e32 v156, 1.0, v156
	v_add_f32_e32 v179, 1.0, v179
	v_add_f32_e32 v157, 1.0, v157
	v_add_f32_e32 v180, 1.0, v180
	v_add_f32_e32 v158, 1.0, v158
	v_add_f32_e32 v181, 1.0, v181
	v_add_f32_e32 v159, 1.0, v159
	v_rcp_f32_e32 v178, v178
	v_rcp_f32_e32 v156, v156
	v_rcp_f32_e32 v179, v179
	v_rcp_f32_e32 v157, v157
	v_rcp_f32_e32 v180, v180
	v_rcp_f32_e32 v158, v158
	v_rcp_f32_e32 v181, v181
	v_rcp_f32_e32 v159, v159
	s_nop 0
	v_mul_f32_e32 v186, v20, v178
	v_mul_f32_e32 v187, v21, v156
	v_mul_f32_e32 v188, v22, v179
	v_mul_f32_e32 v189, v23, v157
	v_mul_f32_e32 v190, v16, v180
	v_mul_f32_e32 v191, v17, v158
	v_mul_f32_e32 v192, v18, v181
	v_mul_f32_e32 v193, v19, v159
	v_cvt_pk_bf16_f32 v156, v186, v187
	v_cvt_pk_bf16_f32 v157, v188, v189
	v_cvt_pk_bf16_f32 v158, v190, v191
	v_cvt_pk_bf16_f32 v159, v192, v193
	global_store_dwordx4 v[210:211], v[156:159], off offset:256
	s_mov_b64 s[98:99], 0x21c000
	v_lshl_add_u64 v[210:211], v[216:217], 0, s[98:99]
	v_lshlrev_b32_e32 v178, 16, v160
	v_and_b32_e32 v160, 0xffff0000, v160
	v_lshlrev_b32_e32 v179, 16, v161
	v_and_b32_e32 v161, 0xffff0000, v161
	v_lshlrev_b32_e32 v180, 16, v162
	v_and_b32_e32 v162, 0xffff0000, v162
	v_lshlrev_b32_e32 v181, 16, v163
	v_and_b32_e32 v163, 0xffff0000, v163
	v_mul_f32_e32 v178, 0xbfb8aa3b, v178
	v_mul_f32_e32 v160, 0xbfb8aa3b, v160
	v_mul_f32_e32 v179, 0xbfb8aa3b, v179
	v_mul_f32_e32 v161, 0xbfb8aa3b, v161
	v_mul_f32_e32 v180, 0xbfb8aa3b, v180
	v_mul_f32_e32 v162, 0xbfb8aa3b, v162
	v_mul_f32_e32 v181, 0xbfb8aa3b, v181
	v_mul_f32_e32 v163, 0xbfb8aa3b, v163
	v_exp_f32_e32 v178, v178
	v_exp_f32_e32 v160, v160
	v_exp_f32_e32 v179, v179
	v_exp_f32_e32 v161, v161
	v_exp_f32_e32 v180, v180
	v_exp_f32_e32 v162, v162
	v_exp_f32_e32 v181, v181
	v_exp_f32_e32 v163, v163
	v_add_f32_e32 v178, 1.0, v178
	v_add_f32_e32 v160, 1.0, v160
	v_add_f32_e32 v179, 1.0, v179
	v_add_f32_e32 v161, 1.0, v161
	v_add_f32_e32 v180, 1.0, v180
	v_add_f32_e32 v162, 1.0, v162
	v_add_f32_e32 v181, 1.0, v181
	v_add_f32_e32 v163, 1.0, v163
	v_rcp_f32_e32 v178, v178
	v_rcp_f32_e32 v160, v160
	v_rcp_f32_e32 v179, v179
	v_rcp_f32_e32 v161, v161
	v_rcp_f32_e32 v180, v180
	v_rcp_f32_e32 v162, v162
	v_rcp_f32_e32 v181, v181
	v_rcp_f32_e32 v163, v163
	s_nop 0
	v_mul_f32_e32 v186, v44, v178
	v_mul_f32_e32 v187, v45, v160
	v_mul_f32_e32 v188, v46, v179
	v_mul_f32_e32 v189, v47, v161
	v_mul_f32_e32 v190, v40, v180
	v_mul_f32_e32 v191, v41, v162
	v_mul_f32_e32 v192, v42, v181
	v_mul_f32_e32 v193, v43, v163
	v_cvt_pk_bf16_f32 v160, v186, v187
	v_cvt_pk_bf16_f32 v161, v188, v189
	v_cvt_pk_bf16_f32 v162, v190, v191
	v_cvt_pk_bf16_f32 v163, v192, v193
	global_store_dwordx4 v[210:211], v[160:163], off
	v_lshlrev_b32_e32 v178, 16, v164
	v_and_b32_e32 v164, 0xffff0000, v164
	v_lshlrev_b32_e32 v179, 16, v165
	v_and_b32_e32 v165, 0xffff0000, v165
	v_lshlrev_b32_e32 v180, 16, v166
	v_and_b32_e32 v166, 0xffff0000, v166
	v_lshlrev_b32_e32 v181, 16, v167
	v_and_b32_e32 v167, 0xffff0000, v167
	v_mul_f32_e32 v178, 0xbfb8aa3b, v178
	v_mul_f32_e32 v164, 0xbfb8aa3b, v164
	v_mul_f32_e32 v179, 0xbfb8aa3b, v179
	v_mul_f32_e32 v165, 0xbfb8aa3b, v165
	v_mul_f32_e32 v180, 0xbfb8aa3b, v180
	v_mul_f32_e32 v166, 0xbfb8aa3b, v166
	v_mul_f32_e32 v181, 0xbfb8aa3b, v181
	v_mul_f32_e32 v167, 0xbfb8aa3b, v167
	v_exp_f32_e32 v178, v178
	v_exp_f32_e32 v164, v164
	v_exp_f32_e32 v179, v179
	v_exp_f32_e32 v165, v165
	v_exp_f32_e32 v180, v180
	v_exp_f32_e32 v166, v166
	v_exp_f32_e32 v181, v181
	v_exp_f32_e32 v167, v167
	v_add_f32_e32 v178, 1.0, v178
	v_add_f32_e32 v164, 1.0, v164
	v_add_f32_e32 v179, 1.0, v179
	v_add_f32_e32 v165, 1.0, v165
	v_add_f32_e32 v180, 1.0, v180
	v_add_f32_e32 v166, 1.0, v166
	v_add_f32_e32 v181, 1.0, v181
	v_add_f32_e32 v167, 1.0, v167
	v_rcp_f32_e32 v178, v178
	v_rcp_f32_e32 v164, v164
	v_rcp_f32_e32 v179, v179
	v_rcp_f32_e32 v165, v165
	v_rcp_f32_e32 v180, v180
	v_rcp_f32_e32 v166, v166
	v_rcp_f32_e32 v181, v181
	v_rcp_f32_e32 v167, v167
	s_nop 0
	v_mul_f32_e32 v186, v12, v178
	v_mul_f32_e32 v187, v13, v164
	v_mul_f32_e32 v188, v14, v179
	v_mul_f32_e32 v189, v15, v165
	v_mul_f32_e32 v190, v8, v180
	v_mul_f32_e32 v191, v9, v166
	v_mul_f32_e32 v192, v10, v181
	v_mul_f32_e32 v193, v11, v167
	v_cvt_pk_bf16_f32 v164, v186, v187
	v_cvt_pk_bf16_f32 v165, v188, v189
	v_cvt_pk_bf16_f32 v166, v190, v191
	v_cvt_pk_bf16_f32 v167, v192, v193
	global_store_dwordx4 v[210:211], v[164:167], off offset:256
	s_mov_b64 s[98:99], 0x252000
	v_lshl_add_u64 v[210:211], v[216:217], 0, s[98:99]
	v_lshlrev_b32_e32 v178, 16, v170
	v_and_b32_e32 v170, 0xffff0000, v170
	v_lshlrev_b32_e32 v179, 16, v171
	v_and_b32_e32 v171, 0xffff0000, v171
	v_lshlrev_b32_e32 v180, 16, v172
	v_and_b32_e32 v172, 0xffff0000, v172
	v_lshlrev_b32_e32 v181, 16, v173
	v_and_b32_e32 v173, 0xffff0000, v173
	v_mul_f32_e32 v178, 0xbfb8aa3b, v178
	v_mul_f32_e32 v170, 0xbfb8aa3b, v170
	v_mul_f32_e32 v179, 0xbfb8aa3b, v179
	v_mul_f32_e32 v171, 0xbfb8aa3b, v171
	v_mul_f32_e32 v180, 0xbfb8aa3b, v180
	v_mul_f32_e32 v172, 0xbfb8aa3b, v172
	v_mul_f32_e32 v181, 0xbfb8aa3b, v181
	v_mul_f32_e32 v173, 0xbfb8aa3b, v173
	v_exp_f32_e32 v178, v178
	v_exp_f32_e32 v170, v170
	v_exp_f32_e32 v179, v179
	v_exp_f32_e32 v171, v171
	v_exp_f32_e32 v180, v180
	v_exp_f32_e32 v172, v172
	v_exp_f32_e32 v181, v181
	v_exp_f32_e32 v173, v173
	v_add_f32_e32 v178, 1.0, v178
	v_add_f32_e32 v170, 1.0, v170
	v_add_f32_e32 v179, 1.0, v179
	v_add_f32_e32 v171, 1.0, v171
	v_add_f32_e32 v180, 1.0, v180
	v_add_f32_e32 v172, 1.0, v172
	v_add_f32_e32 v181, 1.0, v181
	v_add_f32_e32 v173, 1.0, v173
	v_rcp_f32_e32 v178, v178
	v_rcp_f32_e32 v170, v170
	v_rcp_f32_e32 v179, v179
	v_rcp_f32_e32 v171, v171
	v_rcp_f32_e32 v180, v180
	v_rcp_f32_e32 v172, v172
	v_rcp_f32_e32 v181, v181
	v_rcp_f32_e32 v173, v173
	s_nop 0
	v_mul_f32_e32 v186, v36, v178
	v_mul_f32_e32 v187, v37, v170
	v_mul_f32_e32 v188, v38, v179
	v_mul_f32_e32 v189, v39, v171
	v_mul_f32_e32 v190, v32, v180
	v_mul_f32_e32 v191, v33, v172
	v_mul_f32_e32 v192, v34, v181
	v_mul_f32_e32 v193, v35, v173
	v_cvt_pk_bf16_f32 v170, v186, v187
	v_cvt_pk_bf16_f32 v171, v188, v189
	v_cvt_pk_bf16_f32 v172, v190, v191
	v_cvt_pk_bf16_f32 v173, v192, v193
	global_store_dwordx4 v[210:211], v[170:173], off
	v_lshlrev_b32_e32 v178, 16, v174
	v_and_b32_e32 v174, 0xffff0000, v174
	v_lshlrev_b32_e32 v179, 16, v175
	v_and_b32_e32 v175, 0xffff0000, v175
	v_lshlrev_b32_e32 v180, 16, v176
	v_and_b32_e32 v176, 0xffff0000, v176
	v_lshlrev_b32_e32 v181, 16, v177
	v_and_b32_e32 v177, 0xffff0000, v177
	v_mul_f32_e32 v178, 0xbfb8aa3b, v178
	v_mul_f32_e32 v174, 0xbfb8aa3b, v174
	v_mul_f32_e32 v179, 0xbfb8aa3b, v179
	v_mul_f32_e32 v175, 0xbfb8aa3b, v175
	v_mul_f32_e32 v180, 0xbfb8aa3b, v180
	v_mul_f32_e32 v176, 0xbfb8aa3b, v176
	v_mul_f32_e32 v181, 0xbfb8aa3b, v181
	v_mul_f32_e32 v177, 0xbfb8aa3b, v177
	v_exp_f32_e32 v178, v178
	v_exp_f32_e32 v174, v174
	v_exp_f32_e32 v179, v179
	v_exp_f32_e32 v175, v175
	v_exp_f32_e32 v180, v180
	v_exp_f32_e32 v176, v176
	v_exp_f32_e32 v181, v181
	v_exp_f32_e32 v177, v177
	v_add_f32_e32 v178, 1.0, v178
	v_add_f32_e32 v174, 1.0, v174
	v_add_f32_e32 v179, 1.0, v179
	v_add_f32_e32 v175, 1.0, v175
	v_add_f32_e32 v180, 1.0, v180
	v_add_f32_e32 v176, 1.0, v176
	v_add_f32_e32 v181, 1.0, v181
	v_add_f32_e32 v177, 1.0, v177
	v_rcp_f32_e32 v178, v178
	v_rcp_f32_e32 v174, v174
	v_rcp_f32_e32 v179, v179
	v_rcp_f32_e32 v175, v175
	v_rcp_f32_e32 v180, v180
	v_rcp_f32_e32 v176, v176
	v_rcp_f32_e32 v181, v181
	v_rcp_f32_e32 v177, v177
	s_nop 0
	v_mul_f32_e32 v186, v4, v178
	v_mul_f32_e32 v187, v5, v174
	v_mul_f32_e32 v188, v6, v179
	v_mul_f32_e32 v189, v7, v175
	v_mul_f32_e32 v190, v0, v180
	v_mul_f32_e32 v191, v1, v176
	v_mul_f32_e32 v192, v2, v181
	v_mul_f32_e32 v193, v3, v177
	v_cvt_pk_bf16_f32 v174, v186, v187
	v_cvt_pk_bf16_f32 v175, v188, v189
	v_cvt_pk_bf16_f32 v176, v190, v191
	v_cvt_pk_bf16_f32 v177, v192, v193
	global_store_dwordx4 v[210:211], v[174:177], off offset:256
	v_readlane_b32 s98, v254, 40
	s_nop 3
	s_cmp_lg_u32 s98, 0
	s_cbranch_scc1 .Lmgepi_done
	s_waitcnt vmcnt(0)
	s_mov_b64 s[6:7], exec
	s_mov_b64 exec, 1
	v_mov_b32_e32 v178, 0x22320
	v_mov_b32_e32 v179, 1
	ds_add_rtn_u32 v178, v178, v179
	s_waitcnt lgkmcnt(0)
	v_readfirstlane_b32 s98, v178
	s_and_b32 s98, s98, 7
	s_cmp_lg_u32 s98, 7
	s_cbranch_scc1 .Lmgepi_pub_skip
	v_readlane_b32 s98, v255, 30
	s_nop 3
	s_cmp_lg_u32 s98, 0
	s_cselect_b32 s100, 0x200, 0
	s_cmp_ge_u32 s58, 6
	s_cbranch_scc1 .Lmgepi_pub_r2
	s_lshr_b32 s101, s100, 7
	v_readlane_b32 s98, v253, 3
	v_readlane_b32 s99, v253, 4
	s_nop 3
	s_add_u32 s98, s98, s101
	s_addc_u32 s99, s99, 0
	s_nop 4
	global_atomic_add v178, v113, v179, s[98:99] offset:64 sc0
	v_mov_b32_e32 v180, 0x22300
	ds_read_b32 v180, v180
	s_waitcnt vmcnt(0) lgkmcnt(0)
	v_add_u32_e32 v178, 1, v178
	v_cmp_eq_u32_e32 vcc, v178, v180
	s_cbranch_vccz .Lmgepi_pub_skip
	buffer_wbl2 sc1
	s_waitcnt vmcnt(0)
	s_add_u32 s100, s100, 0x8000
	s_add_u32 s98, s88, s100
	s_addc_u32 s99, s89, 0
	s_nop 4
	global_atomic_add v113, v179, s[98:99]
	s_branch .Lmgepi_pub_skip
.Lmgepi_pub_r2:
	buffer_wbl2 sc1
	s_waitcnt vmcnt(0)
	s_add_u32 s100, s100, 0x8080
	s_add_u32 s98, s88, s100
	s_addc_u32 s99, s89, 0
	s_nop 4
	global_atomic_add v113, v179, s[98:99]

.Lwo_sched_set:
	v_writelane_b32 v255, s7, 8
	s_and_b32 s10, s82, 7
	s_mul_i32 s10, s10, 34
	s_lshr_b32 s11, s82, 3
	s_add_u32 s10, s10, s11
	s_lshr_b32 s11, s10, 4
	s_lshl_b32 s11, s11, 2
	s_and_b32 s12, s10, 3
	s_add_u32 s11, s11, s12
	s_bfe_u32 s12, s10, 0x20002
	v_writelane_b32 v255, s11, 12
	v_writelane_b32 v255, s12, 13
	s_lshl_b32 s34, s12, 19
	v_writelane_b32 v255, s34, 15
	s_mov_b32 s34, 0
	s_nop 0
	v_writelane_b32 v255, s34, 16
	s_lshr_b32 s10, s11, 3
	s_bfe_u32 s12, s11, 0x20001
	s_sub_u32 s38, s10, 1
	s_and_b32 s38, s38, 1
	s_cmp_eq_u32 s12, s38
	s_cselect_b32 s34, 1, 0
	s_cmp_eq_u32 s10, 0
	s_cselect_b32 s34, 0, s34
	s_cmp_lt_u32 s39, 16
	s_cselect_b32 s34, 1, s34
	v_readfirstlane_b32 s10, v246
	s_cmp_ge_u32 s10, 64
	s_cbranch_scc1 .Lwo_wait_done
	v_mov_b32_e32 v0, 0x22304
	ds_read_b32 v0, v0
	v_readlane_b32 s98, v255, 30
	s_nop 3
	s_cmp_lg_u32 s98, 0
	s_cselect_b32 s38, 0x200, 0
	s_add_u32 s38, s38, 0x8000
	s_add_u32 s98, s88, s38
	s_addc_u32 s99, s89, 0
	s_waitcnt lgkmcnt(0)
	v_readfirstlane_b32 s12, v0
	s_mov_b32 s7, 0
.Lwo_wait_a:
	global_load_dword v1, v113, s[98:99] sc1
	s_waitcnt vmcnt(0)
	v_readfirstlane_b32 s10, v1
	s_add_u32 s7, s7, 1
	s_cmp_ge_u32 s10, s12
	s_cbranch_scc1 .Lwo_wait_a_done
	s_sleep 2
	s_cmp_lt_u32 s7, 0x4000
	s_cbranch_scc1 .Lwo_wait_a
.Lwo_wait_a_done:
	s_cmp_eq_u32 s34, 0
	s_cbranch_scc1 .Lwo_wait_b_done
	s_mov_b32 s7, 0
.Lwo_wait_b:
	global_load_dword v1, v113, s[98:99] offset:128 sc1
	s_waitcnt vmcnt(0)
	v_readfirstlane_b32 s10, v1
	s_add_u32 s7, s7, 1
	s_cmp_ge_u32 s10, 16
	s_cbranch_scc1 .Lwo_wait_b_done
	s_sleep 2
	s_cmp_lt_u32 s7, 0x4000
	s_cbranch_scc1 .Lwo_wait_b
.Lwo_wait_b_done:
	buffer_inv sc1
	s_waitcnt vmcnt(0)
.Lwo_wait_done:
	s_barrier
.Lwo_sched_done:
	s_add_u32 s2, s88, 0x4a00000
	v_mov_b32_e32 v16, v246
	s_addc_u32 s3, s89, 0
	s_and_b64 vcc, exec, s[42:43]
	v_readfirstlane_b32 s6, v16
	s_cbranch_vccnz .LBB0_1567
	v_lshlrev_b32_e32 v0, 4, v16
	v_add_u32_e32 v1, 0x2000, v0
	v_ashrrev_i32_e32 v2, 31, v1
	v_lshrrev_b32_e32 v2, 22, v2
	v_add_u32_e32 v2, v1, v2
	v_ashrrev_i32_e32 v8, 10, v2
	v_mul_i32_i24_e32 v2, 0x400, v8
	v_sub_u32_e32 v1, v1, v2
	v_lshrrev_b32_e32 v2, 4, v1
	v_bitop3_b32 v1, v2, v1, 32 bitop3:0x6c
	s_ashr_i32 s7, s6, 6
	v_ashrrev_i32_e32 v2, 31, v1
	s_ashr_i32 s12, s6, 8
	s_lshl_b32 s34, s7, 10
	v_lshrrev_b32_e32 v2, 26, v2
	s_add_u32 s38, s88, 0x7601000
	v_add_u32_e32 v2, v1, v2
	v_lshlrev_b32_e32 v3, 3, v8
	s_addc_u32 s39, s89, 0
	v_readlane_b32 s10, v255, 27
	v_ashrrev_i32_e32 v9, 6, v2
	v_and_b32_e32 v3, -16, v3
	s_add_u32 s46, s10, 0x11d0000
	v_readlane_b32 s10, v255, 28
	v_add_u32_e32 v3, v9, v3
	s_addc_u32 s47, s10, 0
	v_and_b32_e32 v4, 3, v9
	s_mov_b32 s10, 0x1fffe0
	v_lshrrev_b32_e32 v5, 2, v3
	v_lshlrev_b32_e32 v6, 1, v3
	v_and_b32_e32 v2, 0xc0, v2
	v_and_or_b32 v4, v3, s10, v4
	v_and_b32_e32 v5, 4, v5
	v_and_b32_e32 v6, 24, v6
	v_sub_u32_e32 v1, v1, v2
	v_or3_b32 v4, v4, v5, v6
	v_lshlrev_b32_e32 v5, 5, v8
	v_ashrrev_i16_sdwa v1, v196, sext(v1) dst_sel:DWORD dst_unused:UNUSED_PAD src0_sel:DWORD src1_sel:BYTE_0
	v_and_b32_e32 v10, 32, v5
	v_bfe_i32 v11, v1, 0, 16
	v_add_u32_e32 v1, v10, v11
	v_lshlrev_b32_e32 v2, 1, v1
	s_movk_i32 s11, 0x1b00
	v_lshl_add_u32 v162, v4, 11, v2
	v_mul_lo_u32 v2, v3, s11
	v_add_lshl_u32 v164, v1, v2, 1
	v_bfe_i32 v1, v16, 27, 1
	v_lshrrev_b32_e32 v1, 22, v1
	v_add_u32_e32 v1, v0, v1
	v_and_b32_e32 v1, 0xfffffc00, v1
	v_sub_u32_e32 v0, v0, v1
	v_lshrrev_b32_e32 v1, 4, v0
	v_ashrrev_i32_e32 v2, 31, v16
	v_bitop3_b32 v0, v1, v0, 32 bitop3:0x6c
	v_lshrrev_b32_e32 v2, 26, v2
	v_ashrrev_i32_e32 v1, 31, v0
	v_add_u32_e32 v2, v16, v2
	v_lshrrev_b32_e32 v1, 26, v1
	v_ashrrev_i32_e32 v13, 6, v2
	v_add_u32_e32 v1, v0, v1
	v_lshlrev_b32_e32 v2, 3, v13
	v_ashrrev_i32_e32 v12, 6, v1
	v_and_b32_e32 v2, -16, v2
	v_add_u32_e32 v2, v12, v2
	v_and_b32_e32 v3, 3, v12
	v_lshrrev_b32_e32 v4, 2, v2
	v_lshlrev_b32_e32 v5, 1, v2
	v_and_b32_e32 v1, 0xc0, v1
	v_and_or_b32 v3, v2, s10, v3
	v_and_b32_e32 v4, 4, v4
	v_and_b32_e32 v5, 24, v5
	v_sub_u32_e32 v0, v0, v1
	v_or3_b32 v3, v3, v4, v5
	v_lshlrev_b32_e32 v4, 5, v13
	v_ashrrev_i16_sdwa v0, v196, sext(v0) dst_sel:DWORD dst_unused:UNUSED_PAD src0_sel:DWORD src1_sel:BYTE_0
	v_and_b32_e32 v14, 32, v4
	v_bfe_i32 v15, v0, 0, 16
	v_add_u32_e32 v0, v14, v15
	v_lshlrev_b32_e32 v1, 1, v0
	v_lshl_add_u32 v112, v3, 11, v1
	v_mul_lo_u32 v1, v2, s11
	v_readlane_b32 s10, v255, 15
	v_readlane_b32 s11, v255, 16
	s_add_u32 s40, s46, s10
	s_addc_u32 s41, s47, s11
	s_add_i32 s48, s34, 0
	s_add_i32 m0, s48, 0x10000
	v_add_lshl_u32 v166, v0, v1, 1
	global_load_lds_dwordx4 v112, s[40:41]
	s_add_i32 m0, s48, 0x12000
	s_add_u32 s10, s40, 0x40000
	global_load_lds_dwordx4 v162, s[40:41]
	s_addc_u32 s11, s41, 0
	s_add_i32 m0, s48, 0x14000
	v_mov_b32_e32 v163, v113
	global_load_lds_dwordx4 v112, s[10:11]
	s_add_i32 m0, s48, 0x16000
	v_mov_b32_e32 v167, v113
	global_load_lds_dwordx4 v162, s[10:11]
	v_readlane_b32 s11, v255, 12
	s_mul_i32 s10, s11, 0x360000
	s_add_u32 s36, s38, s10
	s_mul_hi_i32 s10, s11, 0x360000
	s_addc_u32 s37, s39, s10
	s_add_i32 s49, s48, 0x2000
	s_mov_b32 m0, s48
	s_add_u32 s10, s36, 0x1b0000
	global_load_lds_dwordx4 v166, s[36:37]
	s_mov_b32 m0, s49
	s_addc_u32 s11, s37, 0
	s_add_i32 s50, s48, 0x4000
	global_load_lds_dwordx4 v164, s[36:37]
	s_mov_b32 m0, s50
	s_add_i32 s51, s48, 0x6000
	global_load_lds_dwordx4 v166, s[10:11]
	s_mov_b32 m0, s51
	v_mov_b32_e32 v165, v113
	global_load_lds_dwordx4 v164, s[10:11]
	s_cmp_eq_u32 s12, 1
	v_lshl_add_u64 v[6:7], s[40:41], 0, v[112:113]
	v_lshl_add_u64 v[4:5], s[40:41], 0, v[162:163]
	v_lshl_add_u64 v[0:1], s[36:37], 0, v[166:167]
	s_cselect_b64 s[10:11], -1, 0
	s_cmp_lg_u32 s12, 1
	v_lshl_add_u64 v[2:3], s[36:37], 0, v[164:165]
	s_cbranch_scc1 .LBB0_1550
	s_barrier

	.amdhsa_kernel _Z10fwd_kernel4Args
		.amdhsa_group_segment_fixed_size 0
		.amdhsa_private_segment_fixed_size 0
		.amdhsa_kernarg_size 488
		.amdhsa_user_sgpr_count 2
		.amdhsa_user_sgpr_dispatch_ptr 0
		.amdhsa_user_sgpr_queue_ptr 0
		.amdhsa_user_sgpr_kernarg_segment_ptr 1
		.amdhsa_user_sgpr_dispatch_id 0
		.amdhsa_user_sgpr_kernarg_preload_length 0
		.amdhsa_user_sgpr_kernarg_preload_offset 0
		.amdhsa_user_sgpr_private_segment_size 0
		.amdhsa_uses_dynamic_stack 0
		.amdhsa_enable_private_segment 0
		.amdhsa_system_sgpr_workgroup_id_x 1
		.amdhsa_system_sgpr_workgroup_id_y 0
		.amdhsa_system_sgpr_workgroup_id_z 0
		.amdhsa_system_sgpr_workgroup_info 0
		.amdhsa_system_vgpr_workitem_id 2
		.amdhsa_next_free_vgpr 256
		.amdhsa_next_free_sgpr 102
		.amdhsa_accum_offset 256
		.amdhsa_reserve_vcc 1
		.amdhsa_float_round_mode_32 0
		.amdhsa_float_round_mode_16_64 0
		.amdhsa_float_denorm_mode_32 3
		.amdhsa_float_denorm_mode_16_64 3
		.amdhsa_dx10_clamp 1
		.amdhsa_ieee_mode 1
		.amdhsa_fp16_overflow 0
		.amdhsa_tg_split 0
		.amdhsa_exception_fp_ieee_invalid_op 0
		.amdhsa_exception_fp_denorm_src 0
		.amdhsa_exception_fp_ieee_div_zero 0
		.amdhsa_exception_fp_ieee_overflow 0
		.amdhsa_exception_fp_ieee_underflow 0
		.amdhsa_exception_fp_ieee_inexact 0
		.amdhsa_exception_int_div_zero 0
	.end_amdhsa_kernel

amdhsa.kernels:
  - .agpr_count:     0
    .args:
      - .offset:         0
        .size:           232
        .value_kind:     by_value
      - .offset:         232
        .size:           4
        .value_kind:     hidden_block_count_x
      - .offset:         236
        .size:           4
        .value_kind:     hidden_block_count_y
      - .offset:         240
        .size:           4
        .value_kind:     hidden_block_count_z
      - .offset:         244
        .size:           2
        .value_kind:     hidden_group_size_x
      - .offset:         246
        .size:           2
        .value_kind:     hidden_group_size_y
      - .offset:         248
        .size:           2
        .value_kind:     hidden_group_size_z
      - .offset:         250
        .size:           2
        .value_kind:     hidden_remainder_x
      - .offset:         252
        .size:           2
        .value_kind:     hidden_remainder_y
      - .offset:         254
        .size:           2
        .value_kind:     hidden_remainder_z
      - .offset:         272
        .size:           8
        .value_kind:     hidden_global_offset_x
      - .offset:         280
        .size:           8
        .value_kind:     hidden_global_offset_y
      - .offset:         288
        .size:           8
        .value_kind:     hidden_global_offset_z
      - .offset:         296
        .size:           2
        .value_kind:     hidden_grid_dims
      - .offset:         320
        .size:           8
        .value_kind:     hidden_multigrid_sync_arg
      - .offset:         352
        .size:           4
        .value_kind:     hidden_dynamic_lds_size
    .group_segment_fixed_size: 0
    .kernarg_segment_align: 8
    .kernarg_segment_size: 488
    .language:       OpenCL C
    .language_version:
      - 2
      - 0
    .max_flat_workgroup_size: 512
    .name:           _Z10fwd_kernel4Args
    .private_segment_fixed_size: 0
    .sgpr_count:     108
    .sgpr_spill_count: 250
    .symbol:         _Z10fwd_kernel4Args.kd
    .uniform_work_group_size: 1
    .uses_dynamic_stack: false
    .vgpr_count:     256
    .vgpr_spill_count: 0
    .wavefront_size: 64
